# P2/P9 factor staging: one batch of 10 loads instead of 4 serial load-wait iterations; on k-inner MFMA order + DPP shuffles
# speedup vs baseline: 1.0087x; 1.0080x over previous
; __device__ __forceinline__ void norm_mod_stage(Frame& F, const float* gain, int shift_chunk, int scale_chunk) {
;     ...
;     for (int b = 0; b < 2; ++b)
; #pragma unroll 1
;         for (int c4 = F.tid; c4 < DM / 4; c4 += NWAVES * 64) {
;             const f32x4 g = ((const f32x4*)gain)[c4], sc = ((const f32x4*)(mod + (size_t)b * NMOD + scale_chunk * DM))[c4], sh = ((const f32x4*)(mod + (size_t)b * NMOD + shift_chunk * DM))[c4];
;             A4[b * (DM / 4) + c4] = g * (1.0f + sc); S4[b * (DM / 4) + c4] = sh; }
;     __syncthreads();
.LBB0_321:
	s_cmp_lt_i32 s86, 3
	s_cselect_b64 s[0:1], -1, 0
	s_cmp_gt_i32 s87, 2
	s_cselect_b64 s[4:5], -1, 0
	s_and_b64 s[0:1], s[0:1], s[4:5]
	s_andn2_b64 vcc, exec, s[0:1]
	s_cbranch_vccnz .LBB0_380
	v_mov_b32_e32 v2, v0
	v_readlane_b32 s12, v252, 2
	v_ashrrev_i32_e32 v3, 31, v2
	s_movk_i32 s0, 0x400
	v_lshlrev_b64 v[4:5], 4, v[2:3]
	v_readlane_b32 s20, v252, 10
	v_readlane_b32 s21, v252, 11
	v_cmp_gt_i32_e64 s[0:1], s0, v2
	v_add_u32_e32 v1, 0xfffffe00, v2
	s_waitcnt vmcnt(0)
	v_lshl_add_u32 v10, v2, 4, 0
	v_lshl_add_u64 v[2:3], s[20:21], 0, v[4:5]
	v_lshl_add_u64 v[4:5], s[82:83], 0, v[4:5]
	s_mov_b64 s[4:5], 0x104000
	s_mov_b32 s10, 0
	v_lshl_add_u64 v[4:5], v[4:5], 0, s[4:5]
	s_mov_b64 s[6:7], -1
	s_mov_b64 s[4:5], 0x2000
	s_movk_i32 s2, 0x1ff
	v_mov_b32_e32 v11, 0x18000
	v_readlane_b32 s13, v252, 3
	v_readlane_b32 s14, v252, 4
	v_readlane_b32 s15, v252, 5
	v_readlane_b32 s16, v252, 6
	v_readlane_b32 s17, v252, 7
	v_readlane_b32 s18, v252, 8
	v_readlane_b32 s19, v252, 9
	v_readlane_b32 s22, v252, 12
	v_readlane_b32 s23, v252, 13
	v_readlane_b32 s24, v252, 14
	v_readlane_b32 s25, v252, 15
	v_readlane_b32 s26, v252, 16
	v_readlane_b32 s27, v252, 17
	v_lshl_add_u64 v[8:9], v[2:3], 0, s[4:5]
	global_load_dwordx4 v[14:17], v[2:3], off
	global_load_dwordx4 v[18:21], v[8:9], off
	v_lshl_add_u64 v[6:7], v[4:5], 0, s[4:5]
	global_load_dwordx4 v[22:25], v[4:5], off
	global_load_dwordx4 v[26:29], v[6:7], off
	s_mov_b64 s[8:9], 0x18000
	v_lshl_add_u64 v[54:55], v[4:5], 0, s[8:9]
	v_lshl_add_u64 v[56:57], v[54:55], 0, s[4:5]
	global_load_dwordx4 v[30:33], v[54:55], off
	global_load_dwordx4 v[34:37], v[56:57], off
	v_add_co_u32_e32 v58, vcc, 0xffffc000, v4
	s_nop 1
	v_addc_co_u32_e32 v59, vcc, -1, v5, vcc
	global_load_dwordx4 v[38:41], v[58:59], off
	v_add_co_u32_e32 v58, vcc, 0xffffc000, v6
	s_nop 1
	v_addc_co_u32_e32 v59, vcc, -1, v7, vcc
	global_load_dwordx4 v[42:45], v[58:59], off
	v_add_co_u32_e32 v58, vcc, 0xffffc000, v54
	s_nop 1
	v_addc_co_u32_e32 v59, vcc, -1, v55, vcc
	global_load_dwordx4 v[46:49], v[58:59], off
	v_add_co_u32_e32 v58, vcc, 0xffffc000, v56
	s_nop 1
	v_addc_co_u32_e32 v59, vcc, -1, v57, vcc
	global_load_dwordx4 v[50:53], v[58:59], off
	s_waitcnt vmcnt(4)
	v_pk_add_f32 v[22:23], v[22:23], 1.0 op_sel_hi:[1,0]
	v_pk_add_f32 v[24:25], v[24:25], 1.0 op_sel_hi:[1,0]
	v_pk_add_f32 v[26:27], v[26:27], 1.0 op_sel_hi:[1,0]
	v_pk_add_f32 v[28:29], v[28:29], 1.0 op_sel_hi:[1,0]
	v_pk_add_f32 v[30:31], v[30:31], 1.0 op_sel_hi:[1,0]
	v_pk_add_f32 v[32:33], v[32:33], 1.0 op_sel_hi:[1,0]
	v_pk_add_f32 v[34:35], v[34:35], 1.0 op_sel_hi:[1,0]
	v_pk_add_f32 v[36:37], v[36:37], 1.0 op_sel_hi:[1,0]
	v_pk_mul_f32 v[22:23], v[14:15], v[22:23]
	v_pk_mul_f32 v[24:25], v[16:17], v[24:25]
	v_pk_mul_f32 v[26:27], v[18:19], v[26:27]
	v_pk_mul_f32 v[28:29], v[20:21], v[28:29]
	v_pk_mul_f32 v[30:31], v[14:15], v[30:31]
	v_pk_mul_f32 v[32:33], v[16:17], v[32:33]
	v_pk_mul_f32 v[34:35], v[18:19], v[34:35]
	v_pk_mul_f32 v[36:37], v[20:21], v[36:37]
	ds_write_b128 v10, v[22:25]
	ds_write_b128 v10, v[26:29] offset:8192
	ds_write_b128 v10, v[30:33] offset:16384
	ds_write_b128 v10, v[34:37] offset:24576
	s_waitcnt vmcnt(0)
	ds_write_b128 v10, v[38:41] offset:32768
	ds_write_b128 v10, v[42:45] offset:40960
	ds_write_b128 v10, v[46:49] offset:49152
	ds_write_b128 v10, v[50:53] offset:57344

; __device__ __forceinline__ void norm_mod_stage(Frame& F, const float* gain, int shift_chunk, int scale_chunk) {
;     ...
;     for (int b = 0; b < 2; ++b)
; #pragma unroll 1
;         for (int c4 = F.tid; c4 < DM / 4; c4 += NWAVES * 64) {
;             const f32x4 g = ((const f32x4*)gain)[c4], sc = ((const f32x4*)(mod + (size_t)b * NMOD + scale_chunk * DM))[c4], sh = ((const f32x4*)(mod + (size_t)b * NMOD + shift_chunk * DM))[c4];
;             A4[b * (DM / 4) + c4] = g * (1.0f + sc); S4[b * (DM / 4) + c4] = sh; }
;     __syncthreads();
.LBB0_1816:
	s_cmp_lt_i32 s86, 10
	s_cselect_b64 s[0:1], -1, 0
	s_cmp_gt_i32 s87, 9
	s_cselect_b64 s[4:5], -1, 0
	s_and_b64 s[0:1], s[0:1], s[4:5]
	s_andn2_b64 vcc, exec, s[0:1]
	s_cbranch_vccnz .LBB0_1875
	v_mov_b32_e32 v2, v0
	v_readlane_b32 s12, v252, 18
	s_waitcnt lgkmcnt(0)
	v_ashrrev_i32_e32 v3, 31, v2
	s_movk_i32 s0, 0x400
	v_lshlrev_b64 v[4:5], 4, v[2:3]
	v_readlane_b32 s24, v252, 30
	v_readlane_b32 s25, v252, 31
	v_cmp_gt_i32_e64 s[0:1], s0, v2
	v_add_u32_e32 v1, 0xfffffe00, v2
	s_waitcnt vmcnt(0)
	v_lshl_add_u32 v10, v2, 4, 0
	v_lshl_add_u64 v[2:3], s[24:25], 0, v[4:5]
	v_lshl_add_u64 v[4:5], s[82:83], 0, v[4:5]
	s_mov_b64 s[4:5], 0x110000
	s_mov_b32 s10, 0
	v_lshl_add_u64 v[4:5], v[4:5], 0, s[4:5]
	s_mov_b64 s[6:7], -1
	s_mov_b64 s[4:5], 0x2000
	s_movk_i32 s2, 0x1ff
	v_mov_b32_e32 v11, 0x18000
	v_readlane_b32 s13, v252, 19
	v_readlane_b32 s14, v252, 20
	v_readlane_b32 s15, v252, 21
	v_readlane_b32 s16, v252, 22
	v_readlane_b32 s17, v252, 23
	v_readlane_b32 s18, v252, 24
	v_readlane_b32 s19, v252, 25
	v_readlane_b32 s20, v252, 26
	v_readlane_b32 s21, v252, 27
	v_readlane_b32 s22, v252, 28
	v_readlane_b32 s23, v252, 29
	v_readlane_b32 s26, v252, 32
	v_readlane_b32 s27, v252, 33
	v_lshl_add_u64 v[8:9], v[2:3], 0, s[4:5]
	global_load_dwordx4 v[14:17], v[2:3], off
	global_load_dwordx4 v[18:21], v[8:9], off
	v_lshl_add_u64 v[6:7], v[4:5], 0, s[4:5]
	global_load_dwordx4 v[22:25], v[4:5], off
	global_load_dwordx4 v[26:29], v[6:7], off
	s_mov_b64 s[8:9], 0x18000
	v_lshl_add_u64 v[54:55], v[4:5], 0, s[8:9]
	v_lshl_add_u64 v[56:57], v[54:55], 0, s[4:5]
	global_load_dwordx4 v[30:33], v[54:55], off
	global_load_dwordx4 v[34:37], v[56:57], off
	v_add_co_u32_e32 v58, vcc, 0xffffc000, v4
	s_nop 1
	v_addc_co_u32_e32 v59, vcc, -1, v5, vcc
	global_load_dwordx4 v[38:41], v[58:59], off
	v_add_co_u32_e32 v58, vcc, 0xffffc000, v6
	s_nop 1
	v_addc_co_u32_e32 v59, vcc, -1, v7, vcc
	global_load_dwordx4 v[42:45], v[58:59], off
	v_add_co_u32_e32 v58, vcc, 0xffffc000, v54
	s_nop 1
	v_addc_co_u32_e32 v59, vcc, -1, v55, vcc
	global_load_dwordx4 v[46:49], v[58:59], off
	v_add_co_u32_e32 v58, vcc, 0xffffc000, v56
	s_nop 1
	v_addc_co_u32_e32 v59, vcc, -1, v57, vcc
	global_load_dwordx4 v[50:53], v[58:59], off
	s_waitcnt vmcnt(4)
	v_pk_add_f32 v[22:23], v[22:23], 1.0 op_sel_hi:[1,0]
	v_pk_add_f32 v[24:25], v[24:25], 1.0 op_sel_hi:[1,0]
	v_pk_add_f32 v[26:27], v[26:27], 1.0 op_sel_hi:[1,0]
	v_pk_add_f32 v[28:29], v[28:29], 1.0 op_sel_hi:[1,0]
	v_pk_add_f32 v[30:31], v[30:31], 1.0 op_sel_hi:[1,0]
	v_pk_add_f32 v[32:33], v[32:33], 1.0 op_sel_hi:[1,0]
	v_pk_add_f32 v[34:35], v[34:35], 1.0 op_sel_hi:[1,0]
	v_pk_add_f32 v[36:37], v[36:37], 1.0 op_sel_hi:[1,0]
	v_pk_mul_f32 v[22:23], v[14:15], v[22:23]
	v_pk_mul_f32 v[24:25], v[16:17], v[24:25]
	v_pk_mul_f32 v[26:27], v[18:19], v[26:27]
	v_pk_mul_f32 v[28:29], v[20:21], v[28:29]
	v_pk_mul_f32 v[30:31], v[14:15], v[30:31]
	v_pk_mul_f32 v[32:33], v[16:17], v[32:33]
	v_pk_mul_f32 v[34:35], v[18:19], v[34:35]
	v_pk_mul_f32 v[36:37], v[20:21], v[36:37]
	ds_write_b128 v10, v[22:25]
	ds_write_b128 v10, v[26:29] offset:8192
	ds_write_b128 v10, v[30:33] offset:16384
	ds_write_b128 v10, v[34:37] offset:24576
	s_waitcnt vmcnt(0)
	ds_write_b128 v10, v[38:41] offset:32768
	ds_write_b128 v10, v[42:45] offset:40960
	ds_write_b128 v10, v[46:49] offset:49152
	ds_write_b128 v10, v[50:53] offset:57344
